# conv-gate epilogue: removed 96 dead zero-init v_mov before row_ror DPP moves (instruction selection in the VALU-bound epilogue), on top of the rewritten barrier
# speedup vs baseline: 1.0092x; 1.0069x over previous
; __device__ __forceinline__ unsigned cvt_pk_bf16(float lo, float hi) { const f32x2_t v = {lo, hi}; return __builtin_bit_cast(unsigned, __builtin_convertvector(v, bf16x2_t)); }
;     __device__ __forceinline__ void operator()(const f32x4 (&acc)[2][2][4][2], const Unit& u, int wr, int wc, int fr, int fq) const {
;         const int lane = threadIdx.x & 63;
;         const int col0 = u.pn * 128 + wc * 32 + 8 * fq;
;         f32x4 w0[2], w1[2], w2[2], bb[2];
; #pragma unroll
;         for (int n = 0; n < 2; ++n) { w0[n] = *(const f32x4*)(cw + col0 + 4 * n); w1[n] = *(const f32x4*)(cw + 2816 + col0 + 4 * n); w2[n] = *(const f32x4*)(cw + 2 * 2816 + col0 + 4 * n); bb[n] = *(const f32x4*)(cb + col0 + 4 * n); }
; #pragma unroll
;         for (int ai = 0; ai < 2; ++ai) {
;             const int gbase = u.pm * 248 + 62 * (2 * ai + wr) - 2;
;             float r1[2][4], r2[2][4];
; #pragma unroll
;             for (int n = 0; n < 2; ++n)
; #pragma unroll
;                 for (int x = 0; x < 4; ++x) { r1[n][x] = 0.f; r2[n][x] = 0.f; }
; #pragma unroll
;             for (int m = 0; m < 4; ++m) {
;                 const int rl = 16 * m + fr, g = gbase + rl, tt = g & 16383;
;                 unsigned pk[4];
; #pragma unroll
;                 for (int n = 0; n < 2; ++n) {
;                     float a[4];
; #pragma unroll
;                     for (int x = 0; x < 4; ++x) {
;                         const float uu = acc[ai][0][m][n][x];
;                         float p1 = PG8_DPP(r1[n][x], uu, 0x111);
;                         float p2 = PG8_DPP(r2[n][x], uu, 0x112);
;                         r1[n][x] = PG8_DPP(0.f, uu, 0x121); r2[n][x] = PG8_DPP(0.f, uu, 0x122);
;                         if (tt < 1) p1 = 0.f;
;                         if (tt < 2) p2 = 0.f;
;                         const float uc = bb[n][x] + w2[n][x] * uu + w1[n][x] * p1 + w0[n][x] * p2;
;                         const float sg = __builtin_amdgcn_rcpf(1.f + __builtin_amdgcn_exp2f(-1.44269504f * uc));
;                         a[x] = uc * sg * acc[ai][1][m][n][x];
;                     }
;                     pk[2 * n] = cvt_pk_bf16(a[0], a[1]); pk[2 * n + 1] = cvt_pk_bf16(a[2], a[3]);
;                 }
;                 if (rl >= 2 && g < Mrows) { u32x4 w; w.x = pk[0]; w.y = pk[1]; w.z = pk[2]; w.w = pk[3]; *(u32x4*)(O + (size_t)g * 2816 + col0) = w; }
;             }
.LBB0_809:
	v_lshl_or_b32 v180, s26, 7, v203
	v_ashrrev_i32_e32 v181, 31, v180
	v_lshlrev_b64 v[64:65], 2, v[180:181]
	v_lshl_add_u64 v[68:69], s[10:11], 0, v[64:65]
	v_lshl_add_u64 v[72:73], s[14:15], 0, v[64:65]
	v_lshl_add_u64 v[76:77], s[16:17], 0, v[64:65]
	v_lshl_add_u64 v[96:97], s[12:13], 0, v[64:65]
	global_load_dwordx4 v[64:67], v[68:69], off offset:16
	global_load_dwordx4 v[80:83], v[68:69], off
	s_nop 0
	global_load_dwordx4 v[68:71], v[72:73], off offset:16
	global_load_dwordx4 v[84:87], v[72:73], off
	s_nop 0
	global_load_dwordx4 v[72:75], v[76:77], off offset:16
	global_load_dwordx4 v[92:95], v[76:77], off
	s_nop 0
	global_load_dwordx4 v[76:79], v[96:97], off offset:16
	s_nop 0
	global_load_dwordx4 v[96:99], v[96:97], off
	s_mul_i32 s21, s80, 0xf8
	s_add_i32 s21, s21, s67
	v_add_u32_e32 v221, s21, v182
	s_mov_b32 s28, 0x8000
	v_mov_b32_e32 v234, v161
	v_mov_b32_e32 v235, v161
	v_mov_b32_e32 v236, v161
	v_mov_b32_e32 v237, v161
	v_mov_b32_e32 v230, v161
	v_mov_b32_e32 v231, v161
	v_mov_b32_e32 v232, v161
	v_mov_b32_e32 v233, v161
	v_mov_b32_e32 v226, v161
	v_mov_b32_e32 v227, v161
	v_mov_b32_e32 v228, v161
	v_mov_b32_e32 v229, v161
	v_mov_b32_e32 v222, v161
	v_mov_b32_e32 v223, v161
	v_mov_b32_e32 v224, v161
	v_mov_b32_e32 v225, v161
	v_cmp_gt_i32_e32 vcc, s28, v221
	v_mov_b32_dpp v234, v156 row_shr:1 row_mask:0xf bank_mask:0xf
	v_mov_b32_dpp v235, v156 row_shr:2 row_mask:0xf bank_mask:0xf
	v_mov_b32_dpp v217, v156 row_ror:1 row_mask:0xf bank_mask:0xf
	v_mov_b32_dpp v218, v156 row_ror:2 row_mask:0xf bank_mask:0xf
	v_mov_b32_dpp v236, v157 row_shr:1 row_mask:0xf bank_mask:0xf
	v_mov_b32_dpp v237, v157 row_shr:2 row_mask:0xf bank_mask:0xf
	v_mov_b32_dpp v219, v157 row_ror:1 row_mask:0xf bank_mask:0xf
	v_mov_b32_dpp v220, v157 row_ror:2 row_mask:0xf bank_mask:0xf
	v_mov_b32_dpp v230, v158 row_shr:1 row_mask:0xf bank_mask:0xf
	v_mov_b32_dpp v231, v158 row_shr:2 row_mask:0xf bank_mask:0xf
	v_mov_b32_dpp v213, v158 row_ror:1 row_mask:0xf bank_mask:0xf
	v_mov_b32_dpp v214, v158 row_ror:2 row_mask:0xf bank_mask:0xf
	v_mov_b32_dpp v232, v159 row_shr:1 row_mask:0xf bank_mask:0xf
	v_mov_b32_dpp v233, v159 row_shr:2 row_mask:0xf bank_mask:0xf
	v_mov_b32_dpp v215, v159 row_ror:1 row_mask:0xf bank_mask:0xf
	v_mov_b32_dpp v216, v159 row_ror:2 row_mask:0xf bank_mask:0xf
	v_mov_b32_dpp v226, v152 row_shr:1 row_mask:0xf bank_mask:0xf
	v_mov_b32_dpp v227, v152 row_shr:2 row_mask:0xf bank_mask:0xf
	v_mov_b32_dpp v209, v152 row_ror:1 row_mask:0xf bank_mask:0xf
	v_mov_b32_dpp v210, v152 row_ror:2 row_mask:0xf bank_mask:0xf
	v_mov_b32_dpp v228, v153 row_shr:1 row_mask:0xf bank_mask:0xf
	v_mov_b32_dpp v229, v153 row_shr:2 row_mask:0xf bank_mask:0xf
	v_mov_b32_dpp v211, v153 row_ror:1 row_mask:0xf bank_mask:0xf
	v_mov_b32_dpp v212, v153 row_ror:2 row_mask:0xf bank_mask:0xf
	v_mov_b32_dpp v222, v154 row_shr:1 row_mask:0xf bank_mask:0xf
	v_mov_b32_dpp v223, v154 row_shr:2 row_mask:0xf bank_mask:0xf
	v_mov_b32_dpp v205, v154 row_ror:1 row_mask:0xf bank_mask:0xf
	v_mov_b32_dpp v206, v154 row_ror:2 row_mask:0xf bank_mask:0xf
	v_mov_b32_dpp v224, v155 row_shr:1 row_mask:0xf bank_mask:0xf
	v_mov_b32_dpp v225, v155 row_shr:2 row_mask:0xf bank_mask:0xf
	v_mov_b32_dpp v207, v155 row_ror:1 row_mask:0xf bank_mask:0xf
	v_mov_b32_dpp v208, v155 row_ror:2 row_mask:0xf bank_mask:0xf
	s_waitcnt vmcnt(0)
	s_and_b64 s[0:1], s[4:5], vcc
	s_and_saveexec_b64 s[26:27], s[0:1]
	s_mov_b32 s86, 0x43160000
	s_movk_i32 s29, 0x1600
	s_cbranch_execz .LBB0_811
	v_and_b32_e32 v195, 0x3fff, v221
	v_cmp_gt_u32_e64 s[0:1], 2, v195
	v_cmp_eq_u32_e32 vcc, 0, v195
	s_nop 0
	v_pk_fma_f32 v[156:157], v[156:157], v[92:93], v[96:97]
	v_cndmask_b32_e64 v238, v235, 0, s[0:1]
	v_cndmask_b32_e64 v235, v236, 0, vcc
	v_cndmask_b32_e64 v234, v234, 0, vcc
	v_cndmask_b32_e64 v239, v237, 0, s[0:1]
	v_pk_fma_f32 v[156:157], v[84:85], v[234:235], v[156:157]
	v_pk_fma_f32 v[158:159], v[158:159], v[94:95], v[98:99]
	v_pk_fma_f32 v[156:157], v[80:81], v[238:239], v[156:157]
	v_cndmask_b32_e64 v236, v231, 0, s[0:1]
	v_mul_f32_e32 v195, 0xbfb8aa3b, v156
	v_exp_f32_e32 v195, v195
	v_mul_f32_e32 v196, 0xbfb8aa3b, v157
	v_exp_f32_e32 v196, v196
	v_cndmask_b32_e64 v231, v232, 0, vcc
	v_cndmask_b32_e64 v230, v230, 0, vcc
	v_cndmask_b32_e64 v237, v233, 0, s[0:1]
	v_pk_fma_f32 v[158:159], v[86:87], v[230:231], v[158:159]
	v_add_f32_e32 v195, 1.0, v195
	v_pk_fma_f32 v[158:159], v[82:83], v[236:237], v[158:159]
	v_rcp_f32_e32 v234, v195
	v_add_f32_e32 v195, 1.0, v196
	v_mul_f32_e32 v196, 0xbfb8aa3b, v158
	v_exp_f32_e32 v196, v196
	v_mul_f32_e32 v197, 0xbfb8aa3b, v159
	v_exp_f32_e32 v197, v197
	v_rcp_f32_e32 v235, v195
	v_add_f32_e32 v195, 1.0, v196
	v_rcp_f32_e32 v230, v195
	v_add_f32_e32 v195, 1.0, v197
	v_rcp_f32_e32 v231, v195
	v_pk_mul_f32 v[156:157], v[156:157], v[234:235]
	v_pk_fma_f32 v[152:153], v[152:153], v[72:73], v[76:77]
	v_pk_mul_f32 v[148:149], v[148:149], v[156:157]
	v_pk_mul_f32 v[156:157], v[158:159], v[230:231]
	v_cvt_pk_bf16_f32 v148, v148, v149
	v_pk_mul_f32 v[150:151], v[150:151], v[156:157]
	v_cndmask_b32_e64 v157, v228, 0, vcc
	v_cndmask_b32_e64 v156, v226, 0, vcc
	v_cvt_pk_bf16_f32 v149, v150, v151
	v_cndmask_b32_e64 v151, v229, 0, s[0:1]
	v_cndmask_b32_e64 v150, v227, 0, s[0:1]
	v_pk_fma_f32 v[152:153], v[68:69], v[156:157], v[152:153]
	v_cndmask_b32_e64 v159, v224, 0, vcc
	v_pk_fma_f32 v[150:151], v[64:65], v[150:151], v[152:153]
	v_cndmask_b32_e64 v158, v222, 0, vcc
	v_mul_f32_e32 v152, 0xbfb8aa3b, v150
	v_exp_f32_e32 v156, v152
	v_mul_f32_e32 v152, 0xbfb8aa3b, v151
	v_exp_f32_e32 v157, v152
	v_pk_fma_f32 v[152:153], v[154:155], v[74:75], v[78:79]
	v_add_f32_e32 v154, 1.0, v156
	v_cndmask_b32_e64 v156, v223, 0, s[0:1]
	v_add_f32_e32 v155, 1.0, v157
	v_cndmask_b32_e64 v157, v225, 0, s[0:1]
	v_pk_fma_f32 v[152:153], v[70:71], v[158:159], v[152:153]
	v_rcp_f32_e32 v154, v154
	v_pk_fma_f32 v[152:153], v[66:67], v[156:157], v[152:153]
	v_rcp_f32_e32 v155, v155
	v_mul_f32_e32 v156, 0xbfb8aa3b, v152
	v_mul_f32_e32 v157, 0xbfb8aa3b, v153
	v_exp_f32_e32 v156, v156
	v_exp_f32_e32 v157, v157
	v_pk_mul_f32 v[150:151], v[150:151], v[154:155]
	v_add_f32_e32 v156, 1.0, v156
	v_add_f32_e32 v157, 1.0, v157
	v_rcp_f32_e32 v156, v156
	v_rcp_f32_e32 v157, v157
	v_pk_mul_f32 v[144:145], v[144:145], v[150:151]
	s_nop 0
	v_cvt_pk_bf16_f32 v150, v144, v145
	v_pk_mul_f32 v[144:145], v[152:153], v[156:157]
	s_nop 0
	v_pk_mul_f32 v[144:145], v[146:147], v[144:145]
	s_nop 0
	v_cvt_pk_bf16_f32 v151, v144, v145
	v_mov_b64_e32 v[144:145], s[60:61]
	v_mad_i64_i32 v[144:145], s[0:1], v221, s29, v[144:145]
	v_lshl_add_u64 v[144:145], v[180:181], 1, v[144:145]
	global_store_dwordx4 v[144:145], v[148:151], off
; __device__ __forceinline__ unsigned cvt_pk_bf16(float lo, float hi) { const f32x2_t v = {lo, hi}; return __builtin_bit_cast(unsigned, __builtin_convertvector(v, bf16x2_t)); }
; #define PG8_DPP(old, src, ctrl) __builtin_bit_cast(float, __builtin_amdgcn_update_dpp(__builtin_bit_cast(int, (float)(old)), __builtin_bit_cast(int, (float)(src)), (ctrl), 0xf, 0xf, false))
;     __device__ __forceinline__ void operator()(const f32x4 (&acc)[2][2][4][2], const Unit& u, int wr, int wc, int fr, int fq) const {
;     ...
;             for (int m = 0; m < 4; ++m) {
;                 const int rl = 16 * m + fr, g = gbase + rl, tt = g & 16383;
;                 unsigned pk[4];
; #pragma unroll
;                 for (int n = 0; n < 2; ++n) {
;                     float a[4];
; #pragma unroll
;                     for (int x = 0; x < 4; ++x) {
;                         const float uu = acc[ai][0][m][n][x];
;                         float p1 = PG8_DPP(r1[n][x], uu, 0x111);
;                         float p2 = PG8_DPP(r2[n][x], uu, 0x112);
;                         r1[n][x] = PG8_DPP(0.f, uu, 0x121); r2[n][x] = PG8_DPP(0.f, uu, 0x122);
;                         if (tt < 1) p1 = 0.f;
;                         if (tt < 2) p2 = 0.f;
;                         const float uc = bb[n][x] + w2[n][x] * uu + w1[n][x] * p1 + w0[n][x] * p2;
;                         const float sg = __builtin_amdgcn_rcpf(1.f + __builtin_amdgcn_exp2f(-1.44269504f * uc));
;                         a[x] = uc * sg * acc[ai][1][m][n][x];
;                     }
;                     pk[2 * n] = cvt_pk_bf16(a[0], a[1]); pk[2 * n + 1] = cvt_pk_bf16(a[2], a[3]);
;                 }
;                 if (rl >= 2 && g < Mrows) { u32x4 w; w.x = pk[0]; w.y = pk[1]; w.z = pk[2]; w.w = pk[3]; *(u32x4*)(O + (size_t)g * 2816 + col0) = w; }
.LBB0_811:
	s_or_b64 exec, exec, s[26:27]
	v_add_u32_e32 v221, s21, v184
	v_mov_b32_dpp v217, v140 row_shr:1 row_mask:0xf bank_mask:0xf
	v_mov_b32_dpp v218, v140 row_shr:2 row_mask:0xf bank_mask:0xf
	v_mov_b32_dpp v156, v140 row_ror:1 row_mask:0xf bank_mask:0xf
	v_mov_b32_dpp v157, v140 row_ror:2 row_mask:0xf bank_mask:0xf
	v_mov_b32_dpp v219, v141 row_shr:1 row_mask:0xf bank_mask:0xf
	v_mov_b32_dpp v220, v141 row_shr:2 row_mask:0xf bank_mask:0xf
	v_mov_b32_dpp v158, v141 row_ror:1 row_mask:0xf bank_mask:0xf
	v_mov_b32_dpp v159, v141 row_ror:2 row_mask:0xf bank_mask:0xf
	v_mov_b32_dpp v213, v142 row_shr:1 row_mask:0xf bank_mask:0xf
	v_mov_b32_dpp v214, v142 row_shr:2 row_mask:0xf bank_mask:0xf
	v_mov_b32_dpp v152, v142 row_ror:1 row_mask:0xf bank_mask:0xf
	v_mov_b32_dpp v153, v142 row_ror:2 row_mask:0xf bank_mask:0xf
	v_mov_b32_dpp v215, v143 row_shr:1 row_mask:0xf bank_mask:0xf
	v_mov_b32_dpp v216, v143 row_shr:2 row_mask:0xf bank_mask:0xf
	v_mov_b32_dpp v154, v143 row_ror:1 row_mask:0xf bank_mask:0xf
	v_mov_b32_dpp v155, v143 row_ror:2 row_mask:0xf bank_mask:0xf
	v_mov_b32_dpp v209, v136 row_shr:1 row_mask:0xf bank_mask:0xf
	v_mov_b32_dpp v210, v136 row_shr:2 row_mask:0xf bank_mask:0xf
	v_mov_b32_dpp v148, v136 row_ror:1 row_mask:0xf bank_mask:0xf
	v_mov_b32_dpp v149, v136 row_ror:2 row_mask:0xf bank_mask:0xf
	v_mov_b32_dpp v211, v137 row_shr:1 row_mask:0xf bank_mask:0xf
	v_mov_b32_dpp v212, v137 row_shr:2 row_mask:0xf bank_mask:0xf
	v_mov_b32_dpp v150, v137 row_ror:1 row_mask:0xf bank_mask:0xf
	v_mov_b32_dpp v151, v137 row_ror:2 row_mask:0xf bank_mask:0xf
	v_mov_b32_dpp v205, v138 row_shr:1 row_mask:0xf bank_mask:0xf
	v_mov_b32_dpp v206, v138 row_shr:2 row_mask:0xf bank_mask:0xf
	v_mov_b32_dpp v144, v138 row_ror:1 row_mask:0xf bank_mask:0xf
	v_mov_b32_dpp v145, v138 row_ror:2 row_mask:0xf bank_mask:0xf
	v_mov_b32_dpp v207, v139 row_shr:1 row_mask:0xf bank_mask:0xf
	v_mov_b32_dpp v208, v139 row_shr:2 row_mask:0xf bank_mask:0xf
	v_mov_b32_dpp v146, v139 row_ror:1 row_mask:0xf bank_mask:0xf
	v_mov_b32_dpp v147, v139 row_ror:2 row_mask:0xf bank_mask:0xf
	v_cmp_gt_i32_e32 vcc, s28, v221
	s_and_saveexec_b64 s[26:27], vcc
	s_cbranch_execz .LBB0_813
	v_and_b32_e32 v195, 0x3fff, v221
	v_cmp_gt_u32_e64 s[0:1], 2, v195
	v_cmp_eq_u32_e32 vcc, 0, v195
	s_nop 0
	v_pk_fma_f32 v[140:141], v[140:141], v[92:93], v[96:97]
	v_cndmask_b32_e64 v222, v218, 0, s[0:1]
	v_cndmask_b32_e64 v219, v219, 0, vcc
	v_cndmask_b32_e64 v218, v217, 0, vcc
	v_cndmask_b32_e64 v223, v220, 0, s[0:1]
	v_pk_fma_f32 v[140:141], v[84:85], v[218:219], v[140:141]
	v_pk_fma_f32 v[142:143], v[142:143], v[94:95], v[98:99]
	v_pk_fma_f32 v[140:141], v[80:81], v[222:223], v[140:141]
	v_cndmask_b32_e64 v217, v216, 0, s[0:1]
	v_mul_f32_e32 v195, 0xbfb8aa3b, v140
	v_exp_f32_e32 v195, v195
	v_mul_f32_e32 v196, 0xbfb8aa3b, v141
	v_exp_f32_e32 v196, v196
	v_cndmask_b32_e64 v216, v214, 0, s[0:1]
	v_cndmask_b32_e64 v215, v215, 0, vcc
	v_cndmask_b32_e64 v214, v213, 0, vcc
	v_pk_fma_f32 v[142:143], v[86:87], v[214:215], v[142:143]
	v_add_f32_e32 v195, 1.0, v195
	v_pk_fma_f32 v[142:143], v[82:83], v[216:217], v[142:143]
	v_rcp_f32_e32 v218, v195
	v_add_f32_e32 v195, 1.0, v196
	v_mul_f32_e32 v196, 0xbfb8aa3b, v142
	v_exp_f32_e32 v196, v196
	v_mul_f32_e32 v197, 0xbfb8aa3b, v143
	v_exp_f32_e32 v197, v197
	v_rcp_f32_e32 v219, v195
	v_add_f32_e32 v195, 1.0, v196
	v_rcp_f32_e32 v214, v195
	v_add_f32_e32 v195, 1.0, v197
	v_rcp_f32_e32 v215, v195
	v_pk_mul_f32 v[140:141], v[140:141], v[218:219]
	v_pk_fma_f32 v[136:137], v[136:137], v[72:73], v[76:77]
	v_pk_mul_f32 v[132:133], v[132:133], v[140:141]
	v_pk_mul_f32 v[140:141], v[142:143], v[214:215]
	v_cvt_pk_bf16_f32 v132, v132, v133
	v_pk_mul_f32 v[134:135], v[134:135], v[140:141]
	v_cndmask_b32_e64 v141, v211, 0, vcc
	v_cndmask_b32_e64 v140, v209, 0, vcc
	v_cvt_pk_bf16_f32 v133, v134, v135
	v_cndmask_b32_e64 v135, v212, 0, s[0:1]
	v_cndmask_b32_e64 v134, v210, 0, s[0:1]
	v_pk_fma_f32 v[136:137], v[68:69], v[140:141], v[136:137]
	v_cndmask_b32_e64 v143, v207, 0, vcc
	v_pk_fma_f32 v[134:135], v[64:65], v[134:135], v[136:137]
	v_cndmask_b32_e64 v142, v205, 0, vcc
	v_mul_f32_e32 v136, 0xbfb8aa3b, v134
	v_exp_f32_e32 v140, v136
	v_mul_f32_e32 v136, 0xbfb8aa3b, v135
	v_exp_f32_e32 v141, v136
	v_pk_fma_f32 v[136:137], v[138:139], v[74:75], v[78:79]
	v_add_f32_e32 v138, 1.0, v140
	v_cndmask_b32_e64 v140, v206, 0, s[0:1]
	v_add_f32_e32 v139, 1.0, v141
	v_cndmask_b32_e64 v141, v208, 0, s[0:1]
	v_pk_fma_f32 v[136:137], v[70:71], v[142:143], v[136:137]
	v_rcp_f32_e32 v138, v138
	v_pk_fma_f32 v[136:137], v[66:67], v[140:141], v[136:137]
	v_rcp_f32_e32 v139, v139
	v_mul_f32_e32 v140, 0xbfb8aa3b, v136
	v_mul_f32_e32 v141, 0xbfb8aa3b, v137
	v_exp_f32_e32 v140, v140
	v_exp_f32_e32 v141, v141
	v_pk_mul_f32 v[134:135], v[134:135], v[138:139]
	v_add_f32_e32 v140, 1.0, v140
	v_add_f32_e32 v141, 1.0, v141
	v_rcp_f32_e32 v140, v140
	v_rcp_f32_e32 v141, v141
	v_pk_mul_f32 v[128:129], v[128:129], v[134:135]
	s_nop 0
	v_cvt_pk_bf16_f32 v134, v128, v129
	v_pk_mul_f32 v[128:129], v[136:137], v[140:141]
	s_nop 0
	v_pk_mul_f32 v[128:129], v[130:131], v[128:129]
	s_nop 0
	v_cvt_pk_bf16_f32 v135, v128, v129
	v_mov_b64_e32 v[128:129], s[60:61]
	v_mad_i64_i32 v[128:129], s[0:1], v221, s29, v[128:129]
	v_lshl_add_u64 v[128:129], v[180:181], 1, v[128:129]
	global_store_dwordx4 v[128:129], v[132:135], off
; __device__ __forceinline__ unsigned cvt_pk_bf16(float lo, float hi) { const f32x2_t v = {lo, hi}; return __builtin_bit_cast(unsigned, __builtin_convertvector(v, bf16x2_t)); }
; #define PG8_DPP(old, src, ctrl) __builtin_bit_cast(float, __builtin_amdgcn_update_dpp(__builtin_bit_cast(int, (float)(old)), __builtin_bit_cast(int, (float)(src)), (ctrl), 0xf, 0xf, false))
;     __device__ __forceinline__ void operator()(const f32x4 (&acc)[2][2][4][2], const Unit& u, int wr, int wc, int fr, int fq) const {
;     ...
;             for (int m = 0; m < 4; ++m) {
;                 const int rl = 16 * m + fr, g = gbase + rl, tt = g & 16383;
;                 unsigned pk[4];
; #pragma unroll
;                 for (int n = 0; n < 2; ++n) {
;                     float a[4];
; #pragma unroll
;                     for (int x = 0; x < 4; ++x) {
;                         const float uu = acc[ai][0][m][n][x];
;                         float p1 = PG8_DPP(r1[n][x], uu, 0x111);
;                         float p2 = PG8_DPP(r2[n][x], uu, 0x112);
;                         r1[n][x] = PG8_DPP(0.f, uu, 0x121); r2[n][x] = PG8_DPP(0.f, uu, 0x122);
;                         if (tt < 1) p1 = 0.f;
;                         if (tt < 2) p2 = 0.f;
;                         const float uc = bb[n][x] + w2[n][x] * uu + w1[n][x] * p1 + w0[n][x] * p2;
;                         const float sg = __builtin_amdgcn_rcpf(1.f + __builtin_amdgcn_exp2f(-1.44269504f * uc));
;                         a[x] = uc * sg * acc[ai][1][m][n][x];
;                     }
;                     pk[2 * n] = cvt_pk_bf16(a[0], a[1]); pk[2 * n + 1] = cvt_pk_bf16(a[2], a[3]);
;                 }
;                 if (rl >= 2 && g < Mrows) { u32x4 w; w.x = pk[0]; w.y = pk[1]; w.z = pk[2]; w.w = pk[3]; *(u32x4*)(O + (size_t)g * 2816 + col0) = w; }
.LBB0_813:
	s_or_b64 exec, exec, s[26:27]
	v_add_u32_e32 v205, s21, v185
	v_mov_b32_dpp v156, v124 row_shr:1 row_mask:0xf bank_mask:0xf
	v_mov_b32_dpp v157, v124 row_shr:2 row_mask:0xf bank_mask:0xf
	v_mov_b32_dpp v140, v124 row_ror:1 row_mask:0xf bank_mask:0xf
	v_mov_b32_dpp v141, v124 row_ror:2 row_mask:0xf bank_mask:0xf
	v_mov_b32_dpp v158, v125 row_shr:1 row_mask:0xf bank_mask:0xf
	v_mov_b32_dpp v159, v125 row_shr:2 row_mask:0xf bank_mask:0xf
	v_mov_b32_dpp v142, v125 row_ror:1 row_mask:0xf bank_mask:0xf
	v_mov_b32_dpp v143, v125 row_ror:2 row_mask:0xf bank_mask:0xf
	v_mov_b32_dpp v152, v126 row_shr:1 row_mask:0xf bank_mask:0xf
	v_mov_b32_dpp v153, v126 row_shr:2 row_mask:0xf bank_mask:0xf
	v_mov_b32_dpp v136, v126 row_ror:1 row_mask:0xf bank_mask:0xf
	v_mov_b32_dpp v137, v126 row_ror:2 row_mask:0xf bank_mask:0xf
	v_mov_b32_dpp v154, v127 row_shr:1 row_mask:0xf bank_mask:0xf
	v_mov_b32_dpp v155, v127 row_shr:2 row_mask:0xf bank_mask:0xf
	v_mov_b32_dpp v138, v127 row_ror:1 row_mask:0xf bank_mask:0xf
	v_mov_b32_dpp v139, v127 row_ror:2 row_mask:0xf bank_mask:0xf
	v_mov_b32_dpp v148, v120 row_shr:1 row_mask:0xf bank_mask:0xf
	v_mov_b32_dpp v149, v120 row_shr:2 row_mask:0xf bank_mask:0xf
	v_mov_b32_dpp v132, v120 row_ror:1 row_mask:0xf bank_mask:0xf
	v_mov_b32_dpp v133, v120 row_ror:2 row_mask:0xf bank_mask:0xf
	v_mov_b32_dpp v150, v121 row_shr:1 row_mask:0xf bank_mask:0xf
	v_mov_b32_dpp v151, v121 row_shr:2 row_mask:0xf bank_mask:0xf
	v_mov_b32_dpp v134, v121 row_ror:1 row_mask:0xf bank_mask:0xf
	v_mov_b32_dpp v135, v121 row_ror:2 row_mask:0xf bank_mask:0xf
	v_mov_b32_dpp v144, v122 row_shr:1 row_mask:0xf bank_mask:0xf
	v_mov_b32_dpp v145, v122 row_shr:2 row_mask:0xf bank_mask:0xf
	v_mov_b32_dpp v128, v122 row_ror:1 row_mask:0xf bank_mask:0xf
	v_mov_b32_dpp v129, v122 row_ror:2 row_mask:0xf bank_mask:0xf
	v_mov_b32_dpp v146, v123 row_shr:1 row_mask:0xf bank_mask:0xf
	v_mov_b32_dpp v147, v123 row_shr:2 row_mask:0xf bank_mask:0xf
	v_mov_b32_dpp v130, v123 row_ror:1 row_mask:0xf bank_mask:0xf
	v_mov_b32_dpp v131, v123 row_ror:2 row_mask:0xf bank_mask:0xf
	v_cmp_gt_i32_e32 vcc, s28, v205
	s_and_saveexec_b64 s[26:27], vcc
	s_cbranch_execz .LBB0_815
	v_and_b32_e32 v195, 0x3fff, v205
	v_cmp_gt_u32_e64 s[0:1], 2, v195
	v_cmp_eq_u32_e32 vcc, 0, v195
	s_nop 0
	v_pk_fma_f32 v[124:125], v[124:125], v[92:93], v[96:97]
	v_cndmask_b32_e64 v206, v157, 0, s[0:1]
	v_cndmask_b32_e64 v157, v158, 0, vcc
	v_cndmask_b32_e64 v156, v156, 0, vcc
	v_cndmask_b32_e64 v207, v159, 0, s[0:1]
	v_pk_fma_f32 v[124:125], v[84:85], v[156:157], v[124:125]
	v_pk_fma_f32 v[126:127], v[126:127], v[94:95], v[98:99]
	v_cndmask_b32_e64 v158, v153, 0, s[0:1]
	v_cndmask_b32_e64 v153, v154, 0, vcc
	v_cndmask_b32_e64 v152, v152, 0, vcc
	v_pk_fma_f32 v[124:125], v[80:81], v[206:207], v[124:125]
	v_cndmask_b32_e64 v159, v155, 0, s[0:1]
	v_pk_fma_f32 v[126:127], v[86:87], v[152:153], v[126:127]
	v_mul_f32_e32 v156, 0xbfb8aa3b, v124
	v_mul_f32_e32 v157, 0xbfb8aa3b, v125
	v_pk_fma_f32 v[126:127], v[82:83], v[158:159], v[126:127]
	v_exp_f32_e32 v156, v156
	v_exp_f32_e32 v157, v157
	v_mul_f32_e32 v152, 0xbfb8aa3b, v126
	v_mul_f32_e32 v153, 0xbfb8aa3b, v127
	v_exp_f32_e32 v152, v152
	v_exp_f32_e32 v153, v153
	v_add_f32_e32 v156, 1.0, v156
	v_add_f32_e32 v157, 1.0, v157
	v_rcp_f32_e32 v156, v156
	v_rcp_f32_e32 v157, v157
	v_add_f32_e32 v152, 1.0, v152
	v_add_f32_e32 v153, 1.0, v153
	v_rcp_f32_e32 v152, v152
	v_rcp_f32_e32 v153, v153
	v_pk_mul_f32 v[124:125], v[124:125], v[156:157]
	v_pk_fma_f32 v[120:121], v[120:121], v[72:73], v[76:77]
	v_pk_mul_f32 v[116:117], v[116:117], v[124:125]
	v_pk_mul_f32 v[124:125], v[126:127], v[152:153]
	v_cvt_pk_bf16_f32 v116, v116, v117
	v_pk_mul_f32 v[118:119], v[118:119], v[124:125]
	v_cndmask_b32_e64 v125, v150, 0, vcc
	v_cndmask_b32_e64 v124, v148, 0, vcc
	v_cvt_pk_bf16_f32 v117, v118, v119
	v_cndmask_b32_e64 v119, v151, 0, s[0:1]
	v_cndmask_b32_e64 v118, v149, 0, s[0:1]
	v_pk_fma_f32 v[120:121], v[68:69], v[124:125], v[120:121]
	v_cndmask_b32_e64 v127, v146, 0, vcc
	v_pk_fma_f32 v[118:119], v[64:65], v[118:119], v[120:121]
	v_cndmask_b32_e64 v126, v144, 0, vcc
	v_mul_f32_e32 v120, 0xbfb8aa3b, v118
	v_exp_f32_e32 v124, v120
	v_mul_f32_e32 v120, 0xbfb8aa3b, v119
	v_exp_f32_e32 v125, v120
	v_pk_fma_f32 v[120:121], v[122:123], v[74:75], v[78:79]
	v_add_f32_e32 v122, 1.0, v124
	v_cndmask_b32_e64 v124, v145, 0, s[0:1]
	v_add_f32_e32 v123, 1.0, v125
	v_cndmask_b32_e64 v125, v147, 0, s[0:1]
	v_pk_fma_f32 v[120:121], v[70:71], v[126:127], v[120:121]
	v_rcp_f32_e32 v122, v122
	v_pk_fma_f32 v[120:121], v[66:67], v[124:125], v[120:121]
	v_rcp_f32_e32 v123, v123
	v_mul_f32_e32 v124, 0xbfb8aa3b, v120
	v_mul_f32_e32 v125, 0xbfb8aa3b, v121
	v_exp_f32_e32 v124, v124
	v_exp_f32_e32 v125, v125
	v_pk_mul_f32 v[118:119], v[118:119], v[122:123]
	v_add_f32_e32 v124, 1.0, v124
	v_add_f32_e32 v125, 1.0, v125
	v_rcp_f32_e32 v124, v124
	v_rcp_f32_e32 v125, v125
	v_pk_mul_f32 v[112:113], v[112:113], v[118:119]
	s_nop 0
	v_cvt_pk_bf16_f32 v118, v112, v113
	v_pk_mul_f32 v[112:113], v[120:121], v[124:125]
	s_nop 0
	v_pk_mul_f32 v[112:113], v[114:115], v[112:113]
	s_nop 0
	v_cvt_pk_bf16_f32 v119, v112, v113
	v_mov_b64_e32 v[112:113], s[60:61]
	v_mad_i64_i32 v[112:113], s[0:1], v205, s29, v[112:113]
	v_lshl_add_u64 v[112:113], v[180:181], 1, v[112:113]
	global_store_dwordx4 v[112:113], v[116:119], off

; __device__ __forceinline__ unsigned cvt_pk_bf16(float lo, float hi) { const f32x2_t v = {lo, hi}; return __builtin_bit_cast(unsigned, __builtin_convertvector(v, bf16x2_t)); }
; #define PG8_DPP(old, src, ctrl) __builtin_bit_cast(float, __builtin_amdgcn_update_dpp(__builtin_bit_cast(int, (float)(old)), __builtin_bit_cast(int, (float)(src)), (ctrl), 0xf, 0xf, false))
;     __device__ __forceinline__ void operator()(const f32x4 (&acc)[2][2][4][2], const Unit& u, int wr, int wc, int fr, int fq) const {
;     ...
;             for (int m = 0; m < 4; ++m) {
;                 const int rl = 16 * m + fr, g = gbase + rl, tt = g & 16383;
;                 unsigned pk[4];
; #pragma unroll
;                 for (int n = 0; n < 2; ++n) {
;                     float a[4];
; #pragma unroll
;                     for (int x = 0; x < 4; ++x) {
;                         const float uu = acc[ai][0][m][n][x];
;                         float p1 = PG8_DPP(r1[n][x], uu, 0x111);
;                         float p2 = PG8_DPP(r2[n][x], uu, 0x112);
;                         r1[n][x] = PG8_DPP(0.f, uu, 0x121); r2[n][x] = PG8_DPP(0.f, uu, 0x122);
;                         if (tt < 1) p1 = 0.f;
;                         if (tt < 2) p2 = 0.f;
;                         const float uc = bb[n][x] + w2[n][x] * uu + w1[n][x] * p1 + w0[n][x] * p2;
;                         const float sg = __builtin_amdgcn_rcpf(1.f + __builtin_amdgcn_exp2f(-1.44269504f * uc));
;                         a[x] = uc * sg * acc[ai][1][m][n][x];
;                     }
;                     pk[2 * n] = cvt_pk_bf16(a[0], a[1]); pk[2 * n + 1] = cvt_pk_bf16(a[2], a[3]);
;                 }
;                 if (rl >= 2 && g < Mrows) { u32x4 w; w.x = pk[0]; w.y = pk[1]; w.z = pk[2]; w.w = pk[3]; *(u32x4*)(O + (size_t)g * 2816 + col0) = w; }
.LBB0_817:
	s_or_b64 exec, exec, s[26:27]
	s_addk_i32 s21, 0x7c
	v_add_u32_e32 v112, s21, v182
	v_mov_b32_e32 v125, v161
	v_mov_b32_e32 v126, v161
	v_mov_b32_e32 v127, v161
	v_mov_b32_e32 v128, v161
	v_mov_b32_e32 v121, v161
	v_mov_b32_e32 v122, v161
	v_mov_b32_e32 v123, v161
	v_mov_b32_e32 v124, v161
	v_mov_b32_e32 v117, v161
	v_mov_b32_e32 v118, v161
	v_mov_b32_e32 v119, v161
	v_mov_b32_e32 v120, v161
	v_mov_b32_e32 v113, v161
	v_mov_b32_e32 v114, v161
	v_mov_b32_e32 v115, v161
	v_mov_b32_e32 v116, v161
	v_cmp_gt_i32_e32 vcc, s28, v112
	v_mov_b32_dpp v125, v60 row_shr:1 row_mask:0xf bank_mask:0xf
	v_mov_b32_dpp v126, v60 row_shr:2 row_mask:0xf bank_mask:0xf
	v_mov_b32_dpp v108, v60 row_ror:1 row_mask:0xf bank_mask:0xf
	v_mov_b32_dpp v109, v60 row_ror:2 row_mask:0xf bank_mask:0xf
	v_mov_b32_dpp v127, v61 row_shr:1 row_mask:0xf bank_mask:0xf
	v_mov_b32_dpp v128, v61 row_shr:2 row_mask:0xf bank_mask:0xf
	v_mov_b32_dpp v110, v61 row_ror:1 row_mask:0xf bank_mask:0xf
	v_mov_b32_dpp v111, v61 row_ror:2 row_mask:0xf bank_mask:0xf
	v_mov_b32_dpp v121, v62 row_shr:1 row_mask:0xf bank_mask:0xf
	v_mov_b32_dpp v122, v62 row_shr:2 row_mask:0xf bank_mask:0xf
	v_mov_b32_dpp v104, v62 row_ror:1 row_mask:0xf bank_mask:0xf
	v_mov_b32_dpp v105, v62 row_ror:2 row_mask:0xf bank_mask:0xf
	v_mov_b32_dpp v123, v63 row_shr:1 row_mask:0xf bank_mask:0xf
	v_mov_b32_dpp v124, v63 row_shr:2 row_mask:0xf bank_mask:0xf
	v_mov_b32_dpp v106, v63 row_ror:1 row_mask:0xf bank_mask:0xf
	v_mov_b32_dpp v107, v63 row_ror:2 row_mask:0xf bank_mask:0xf
	v_mov_b32_dpp v117, v56 row_shr:1 row_mask:0xf bank_mask:0xf
	v_mov_b32_dpp v118, v56 row_shr:2 row_mask:0xf bank_mask:0xf
	v_mov_b32_dpp v100, v56 row_ror:1 row_mask:0xf bank_mask:0xf
	v_mov_b32_dpp v101, v56 row_ror:2 row_mask:0xf bank_mask:0xf
	v_mov_b32_dpp v119, v57 row_shr:1 row_mask:0xf bank_mask:0xf
	v_mov_b32_dpp v120, v57 row_shr:2 row_mask:0xf bank_mask:0xf
	v_mov_b32_dpp v102, v57 row_ror:1 row_mask:0xf bank_mask:0xf
	v_mov_b32_dpp v103, v57 row_ror:2 row_mask:0xf bank_mask:0xf
	v_mov_b32_dpp v113, v58 row_shr:1 row_mask:0xf bank_mask:0xf
	v_mov_b32_dpp v114, v58 row_shr:2 row_mask:0xf bank_mask:0xf
	v_mov_b32_dpp v88, v58 row_ror:1 row_mask:0xf bank_mask:0xf
	v_mov_b32_dpp v89, v58 row_ror:2 row_mask:0xf bank_mask:0xf
	v_mov_b32_dpp v115, v59 row_shr:1 row_mask:0xf bank_mask:0xf
	v_mov_b32_dpp v116, v59 row_shr:2 row_mask:0xf bank_mask:0xf
	v_mov_b32_dpp v90, v59 row_ror:1 row_mask:0xf bank_mask:0xf
	v_mov_b32_dpp v91, v59 row_ror:2 row_mask:0xf bank_mask:0xf
	s_and_b64 s[0:1], s[4:5], vcc
	s_and_saveexec_b64 s[26:27], s[0:1]
	s_cbranch_execz .LBB0_819
	v_and_b32_e32 v130, 0x3fff, v112
	v_cmp_gt_u32_e64 s[0:1], 2, v130
	v_cmp_eq_u32_e32 vcc, 0, v130
	s_nop 0
	v_pk_fma_f32 v[60:61], v[60:61], v[92:93], v[96:97]
	v_cndmask_b32_e64 v129, v128, 0, s[0:1]
	v_cndmask_b32_e64 v128, v126, 0, s[0:1]
	v_cndmask_b32_e64 v127, v127, 0, vcc
	v_cndmask_b32_e64 v126, v125, 0, vcc
	v_pk_fma_f32 v[60:61], v[84:85], v[126:127], v[60:61]
	v_pk_fma_f32 v[62:63], v[62:63], v[94:95], v[98:99]
	v_pk_fma_f32 v[60:61], v[80:81], v[128:129], v[60:61]
	v_cndmask_b32_e64 v123, v123, 0, vcc
	v_mul_f32_e32 v125, 0xbfb8aa3b, v60
	v_exp_f32_e32 v125, v125
	v_mul_f32_e32 v126, 0xbfb8aa3b, v61
	v_exp_f32_e32 v127, v126
	v_pk_fma_f32 v[56:57], v[56:57], v[72:73], v[76:77]
	v_add_f32_e32 v125, 1.0, v125
	v_rcp_f32_e32 v126, v125
	v_cndmask_b32_e64 v125, v124, 0, s[0:1]
	v_cndmask_b32_e64 v124, v122, 0, s[0:1]
	v_cndmask_b32_e64 v122, v121, 0, vcc
	v_pk_fma_f32 v[62:63], v[86:87], v[122:123], v[62:63]
	v_add_f32_e32 v127, 1.0, v127
	v_pk_fma_f32 v[62:63], v[82:83], v[124:125], v[62:63]
	v_rcp_f32_e32 v127, v127
	v_mul_f32_e32 v121, 0xbfb8aa3b, v62
	v_exp_f32_e32 v121, v121
	v_mul_f32_e32 v122, 0xbfb8aa3b, v63
	v_exp_f32_e32 v123, v122
	v_pk_mul_f32 v[60:61], v[60:61], v[126:127]
	v_add_f32_e32 v121, 1.0, v121
	v_rcp_f32_e32 v122, v121
	v_add_f32_e32 v121, 1.0, v123
	v_rcp_f32_e32 v123, v121
	v_pk_mul_f32 v[52:53], v[52:53], v[60:61]
	v_pk_mul_f32 v[60:61], v[62:63], v[122:123]
	s_nop 0
	v_pk_mul_f32 v[54:55], v[54:55], v[60:61]
	v_cndmask_b32_e64 v61, v119, 0, vcc
	v_cndmask_b32_e64 v60, v117, 0, vcc
	v_cvt_pk_bf16_f32 v52, v52, v53
	v_cvt_pk_bf16_f32 v53, v54, v55
	v_cndmask_b32_e64 v55, v120, 0, s[0:1]
	v_cndmask_b32_e64 v54, v118, 0, s[0:1]
	v_pk_fma_f32 v[56:57], v[68:69], v[60:61], v[56:57]
	v_cndmask_b32_e64 v63, v115, 0, vcc
	v_pk_fma_f32 v[54:55], v[64:65], v[54:55], v[56:57]
	v_cndmask_b32_e64 v62, v113, 0, vcc
	v_mul_f32_e32 v56, 0xbfb8aa3b, v54
	v_exp_f32_e32 v60, v56
	v_mul_f32_e32 v56, 0xbfb8aa3b, v55
	v_exp_f32_e32 v61, v56
	v_pk_fma_f32 v[56:57], v[58:59], v[74:75], v[78:79]
	v_add_f32_e32 v58, 1.0, v60
	v_cndmask_b32_e64 v60, v114, 0, s[0:1]
	v_add_f32_e32 v59, 1.0, v61
	v_cndmask_b32_e64 v61, v116, 0, s[0:1]
	v_pk_fma_f32 v[56:57], v[70:71], v[62:63], v[56:57]
	v_rcp_f32_e32 v58, v58
	v_pk_fma_f32 v[56:57], v[66:67], v[60:61], v[56:57]
	v_rcp_f32_e32 v59, v59
	v_mul_f32_e32 v60, 0xbfb8aa3b, v56
	v_mul_f32_e32 v61, 0xbfb8aa3b, v57
	v_exp_f32_e32 v60, v60
	v_exp_f32_e32 v61, v61
	v_pk_mul_f32 v[54:55], v[54:55], v[58:59]
	v_add_f32_e32 v60, 1.0, v60
	v_add_f32_e32 v61, 1.0, v61
	v_rcp_f32_e32 v60, v60
	v_rcp_f32_e32 v61, v61
	v_pk_mul_f32 v[48:49], v[48:49], v[54:55]
	s_nop 0
	v_cvt_pk_bf16_f32 v54, v48, v49
	v_pk_mul_f32 v[48:49], v[56:57], v[60:61]
	s_nop 0
	v_pk_mul_f32 v[48:49], v[50:51], v[48:49]
	s_nop 0
	v_cvt_pk_bf16_f32 v55, v48, v49
	v_mov_b64_e32 v[48:49], s[60:61]
	v_mad_i64_i32 v[48:49], s[0:1], v112, s29, v[48:49]
	v_lshl_add_u64 v[48:49], v[180:181], 1, v[48:49]
	global_store_dwordx4 v[48:49], v[52:55], off
; __device__ __forceinline__ unsigned cvt_pk_bf16(float lo, float hi) { const f32x2_t v = {lo, hi}; return __builtin_bit_cast(unsigned, __builtin_convertvector(v, bf16x2_t)); }
; #define PG8_DPP(old, src, ctrl) __builtin_bit_cast(float, __builtin_amdgcn_update_dpp(__builtin_bit_cast(int, (float)(old)), __builtin_bit_cast(int, (float)(src)), (ctrl), 0xf, 0xf, false))
;     __device__ __forceinline__ void operator()(const f32x4 (&acc)[2][2][4][2], const Unit& u, int wr, int wc, int fr, int fq) const {
;     ...
;             for (int m = 0; m < 4; ++m) {
;                 const int rl = 16 * m + fr, g = gbase + rl, tt = g & 16383;
;                 unsigned pk[4];
; #pragma unroll
;                 for (int n = 0; n < 2; ++n) {
;                     float a[4];
; #pragma unroll
;                     for (int x = 0; x < 4; ++x) {
;                         const float uu = acc[ai][0][m][n][x];
;                         float p1 = PG8_DPP(r1[n][x], uu, 0x111);
;                         float p2 = PG8_DPP(r2[n][x], uu, 0x112);
;                         r1[n][x] = PG8_DPP(0.f, uu, 0x121); r2[n][x] = PG8_DPP(0.f, uu, 0x122);
;                         if (tt < 1) p1 = 0.f;
;                         if (tt < 2) p2 = 0.f;
;                         const float uc = bb[n][x] + w2[n][x] * uu + w1[n][x] * p1 + w0[n][x] * p2;
;                         const float sg = __builtin_amdgcn_rcpf(1.f + __builtin_amdgcn_exp2f(-1.44269504f * uc));
;                         a[x] = uc * sg * acc[ai][1][m][n][x];
;                     }
;                     pk[2 * n] = cvt_pk_bf16(a[0], a[1]); pk[2 * n + 1] = cvt_pk_bf16(a[2], a[3]);
;                 }
;                 if (rl >= 2 && g < Mrows) { u32x4 w; w.x = pk[0]; w.y = pk[1]; w.z = pk[2]; w.w = pk[3]; *(u32x4*)(O + (size_t)g * 2816 + col0) = w; }
.LBB0_819:
	s_or_b64 exec, exec, s[26:27]
	v_add_u32_e32 v112, s21, v184
	v_mov_b32_dpp v108, v44 row_shr:1 row_mask:0xf bank_mask:0xf
	v_mov_b32_dpp v109, v44 row_shr:2 row_mask:0xf bank_mask:0xf
	v_mov_b32_dpp v60, v44 row_ror:1 row_mask:0xf bank_mask:0xf
	v_mov_b32_dpp v61, v44 row_ror:2 row_mask:0xf bank_mask:0xf
	v_mov_b32_dpp v110, v45 row_shr:1 row_mask:0xf bank_mask:0xf
	v_mov_b32_dpp v111, v45 row_shr:2 row_mask:0xf bank_mask:0xf
	v_mov_b32_dpp v62, v45 row_ror:1 row_mask:0xf bank_mask:0xf
	v_mov_b32_dpp v63, v45 row_ror:2 row_mask:0xf bank_mask:0xf
	v_mov_b32_dpp v104, v46 row_shr:1 row_mask:0xf bank_mask:0xf
	v_mov_b32_dpp v105, v46 row_shr:2 row_mask:0xf bank_mask:0xf
	v_mov_b32_dpp v56, v46 row_ror:1 row_mask:0xf bank_mask:0xf
	v_mov_b32_dpp v57, v46 row_ror:2 row_mask:0xf bank_mask:0xf
	v_mov_b32_dpp v106, v47 row_shr:1 row_mask:0xf bank_mask:0xf
	v_mov_b32_dpp v107, v47 row_shr:2 row_mask:0xf bank_mask:0xf
	v_mov_b32_dpp v58, v47 row_ror:1 row_mask:0xf bank_mask:0xf
	v_mov_b32_dpp v59, v47 row_ror:2 row_mask:0xf bank_mask:0xf
	v_mov_b32_dpp v100, v40 row_shr:1 row_mask:0xf bank_mask:0xf
	v_mov_b32_dpp v101, v40 row_shr:2 row_mask:0xf bank_mask:0xf
	v_mov_b32_dpp v52, v40 row_ror:1 row_mask:0xf bank_mask:0xf
	v_mov_b32_dpp v53, v40 row_ror:2 row_mask:0xf bank_mask:0xf
	v_mov_b32_dpp v102, v41 row_shr:1 row_mask:0xf bank_mask:0xf
	v_mov_b32_dpp v103, v41 row_shr:2 row_mask:0xf bank_mask:0xf
	v_mov_b32_dpp v54, v41 row_ror:1 row_mask:0xf bank_mask:0xf
	v_mov_b32_dpp v55, v41 row_ror:2 row_mask:0xf bank_mask:0xf
	v_mov_b32_dpp v88, v42 row_shr:1 row_mask:0xf bank_mask:0xf
	v_mov_b32_dpp v89, v42 row_shr:2 row_mask:0xf bank_mask:0xf
	v_mov_b32_dpp v48, v42 row_ror:1 row_mask:0xf bank_mask:0xf
	v_mov_b32_dpp v49, v42 row_ror:2 row_mask:0xf bank_mask:0xf
	v_mov_b32_dpp v90, v43 row_shr:1 row_mask:0xf bank_mask:0xf
	v_mov_b32_dpp v91, v43 row_shr:2 row_mask:0xf bank_mask:0xf
	v_mov_b32_dpp v50, v43 row_ror:1 row_mask:0xf bank_mask:0xf
	v_mov_b32_dpp v51, v43 row_ror:2 row_mask:0xf bank_mask:0xf
	v_cmp_gt_i32_e32 vcc, s28, v112
	s_and_saveexec_b64 s[26:27], vcc
	s_cbranch_execz .LBB0_821
	v_and_b32_e32 v113, 0x3fff, v112
	v_cmp_gt_u32_e64 s[0:1], 2, v113
	v_cmp_eq_u32_e32 vcc, 0, v113
	s_nop 0
	v_pk_fma_f32 v[44:45], v[44:45], v[92:93], v[96:97]
	v_cndmask_b32_e64 v114, v109, 0, s[0:1]
	v_cndmask_b32_e64 v109, v110, 0, vcc
	v_cndmask_b32_e64 v108, v108, 0, vcc
	v_cndmask_b32_e64 v115, v111, 0, s[0:1]
	v_pk_fma_f32 v[44:45], v[84:85], v[108:109], v[44:45]
	v_pk_fma_f32 v[46:47], v[46:47], v[94:95], v[98:99]
	v_cndmask_b32_e64 v110, v105, 0, s[0:1]
	v_cndmask_b32_e64 v105, v106, 0, vcc
	v_cndmask_b32_e64 v104, v104, 0, vcc
	v_pk_fma_f32 v[44:45], v[80:81], v[114:115], v[44:45]
	v_cndmask_b32_e64 v111, v107, 0, s[0:1]
	v_pk_fma_f32 v[46:47], v[86:87], v[104:105], v[46:47]
	v_mul_f32_e32 v108, 0xbfb8aa3b, v44
	v_mul_f32_e32 v109, 0xbfb8aa3b, v45
	v_pk_fma_f32 v[46:47], v[82:83], v[110:111], v[46:47]
	v_exp_f32_e32 v108, v108
	v_exp_f32_e32 v109, v109
	v_mul_f32_e32 v104, 0xbfb8aa3b, v46
	v_mul_f32_e32 v105, 0xbfb8aa3b, v47
	v_exp_f32_e32 v104, v104
	v_exp_f32_e32 v105, v105
	v_add_f32_e32 v108, 1.0, v108
	v_add_f32_e32 v109, 1.0, v109
	v_rcp_f32_e32 v108, v108
	v_rcp_f32_e32 v109, v109
	v_add_f32_e32 v104, 1.0, v104
	v_add_f32_e32 v105, 1.0, v105
	v_rcp_f32_e32 v104, v104
	v_rcp_f32_e32 v105, v105
	v_pk_mul_f32 v[44:45], v[44:45], v[108:109]
	v_pk_fma_f32 v[40:41], v[40:41], v[72:73], v[76:77]
	v_pk_mul_f32 v[36:37], v[36:37], v[44:45]
	v_pk_mul_f32 v[44:45], v[46:47], v[104:105]
	v_cvt_pk_bf16_f32 v36, v36, v37
	v_pk_mul_f32 v[38:39], v[38:39], v[44:45]
	v_cndmask_b32_e64 v45, v102, 0, vcc
	v_cndmask_b32_e64 v44, v100, 0, vcc
	v_cvt_pk_bf16_f32 v37, v38, v39
	v_cndmask_b32_e64 v39, v103, 0, s[0:1]
	v_cndmask_b32_e64 v38, v101, 0, s[0:1]
	v_pk_fma_f32 v[40:41], v[68:69], v[44:45], v[40:41]
	v_cndmask_b32_e64 v47, v90, 0, vcc
	v_pk_fma_f32 v[38:39], v[64:65], v[38:39], v[40:41]
	v_cndmask_b32_e64 v46, v88, 0, vcc
	v_mul_f32_e32 v40, 0xbfb8aa3b, v38
	v_exp_f32_e32 v44, v40
	v_mul_f32_e32 v40, 0xbfb8aa3b, v39
	v_exp_f32_e32 v45, v40
	v_pk_fma_f32 v[40:41], v[42:43], v[74:75], v[78:79]
	v_add_f32_e32 v42, 1.0, v44
	v_cndmask_b32_e64 v44, v89, 0, s[0:1]
	v_add_f32_e32 v43, 1.0, v45
	v_cndmask_b32_e64 v45, v91, 0, s[0:1]
	v_pk_fma_f32 v[40:41], v[70:71], v[46:47], v[40:41]
	v_rcp_f32_e32 v42, v42
	v_pk_fma_f32 v[40:41], v[66:67], v[44:45], v[40:41]
	v_rcp_f32_e32 v43, v43
	v_mul_f32_e32 v44, 0xbfb8aa3b, v40
	v_mul_f32_e32 v45, 0xbfb8aa3b, v41
	v_exp_f32_e32 v44, v44
	v_exp_f32_e32 v45, v45
	v_pk_mul_f32 v[38:39], v[38:39], v[42:43]
	v_add_f32_e32 v44, 1.0, v44
	v_add_f32_e32 v45, 1.0, v45
	v_rcp_f32_e32 v44, v44
	v_rcp_f32_e32 v45, v45
	v_pk_mul_f32 v[32:33], v[32:33], v[38:39]
	s_nop 0
	v_cvt_pk_bf16_f32 v38, v32, v33
	v_pk_mul_f32 v[32:33], v[40:41], v[44:45]
	s_nop 0
	v_pk_mul_f32 v[32:33], v[34:35], v[32:33]
	s_nop 0
	v_cvt_pk_bf16_f32 v39, v32, v33
	v_mov_b64_e32 v[32:33], s[60:61]
	v_mad_i64_i32 v[32:33], s[0:1], v112, s29, v[32:33]
	v_lshl_add_u64 v[32:33], v[180:181], 1, v[32:33]
	global_store_dwordx4 v[32:33], v[36:39], off
; __device__ __forceinline__ unsigned cvt_pk_bf16(float lo, float hi) { const f32x2_t v = {lo, hi}; return __builtin_bit_cast(unsigned, __builtin_convertvector(v, bf16x2_t)); }
; #define PG8_DPP(old, src, ctrl) __builtin_bit_cast(float, __builtin_amdgcn_update_dpp(__builtin_bit_cast(int, (float)(old)), __builtin_bit_cast(int, (float)(src)), (ctrl), 0xf, 0xf, false))
;     __device__ __forceinline__ void operator()(const f32x4 (&acc)[2][2][4][2], const Unit& u, int wr, int wc, int fr, int fq) const {
;     ...
;             for (int m = 0; m < 4; ++m) {
;                 const int rl = 16 * m + fr, g = gbase + rl, tt = g & 16383;
;                 unsigned pk[4];
; #pragma unroll
;                 for (int n = 0; n < 2; ++n) {
;                     float a[4];
; #pragma unroll
;                     for (int x = 0; x < 4; ++x) {
;                         const float uu = acc[ai][0][m][n][x];
;                         float p1 = PG8_DPP(r1[n][x], uu, 0x111);
;                         float p2 = PG8_DPP(r2[n][x], uu, 0x112);
;                         r1[n][x] = PG8_DPP(0.f, uu, 0x121); r2[n][x] = PG8_DPP(0.f, uu, 0x122);
;                         if (tt < 1) p1 = 0.f;
;                         if (tt < 2) p2 = 0.f;
;                         const float uc = bb[n][x] + w2[n][x] * uu + w1[n][x] * p1 + w0[n][x] * p2;
;                         const float sg = __builtin_amdgcn_rcpf(1.f + __builtin_amdgcn_exp2f(-1.44269504f * uc));
;                         a[x] = uc * sg * acc[ai][1][m][n][x];
;                     }
;                     pk[2 * n] = cvt_pk_bf16(a[0], a[1]); pk[2 * n + 1] = cvt_pk_bf16(a[2], a[3]);
;                 }
;                 if (rl >= 2 && g < Mrows) { u32x4 w; w.x = pk[0]; w.y = pk[1]; w.z = pk[2]; w.w = pk[3]; *(u32x4*)(O + (size_t)g * 2816 + col0) = w; }
.LBB0_821:
	s_or_b64 exec, exec, s[26:27]
	v_add_u32_e32 v88, s21, v185
	v_mov_b32_dpp v60, v28 row_shr:1 row_mask:0xf bank_mask:0xf
	v_mov_b32_dpp v61, v28 row_shr:2 row_mask:0xf bank_mask:0xf
	v_mov_b32_dpp v44, v28 row_ror:1 row_mask:0xf bank_mask:0xf
	v_mov_b32_dpp v45, v28 row_ror:2 row_mask:0xf bank_mask:0xf
	v_mov_b32_dpp v62, v29 row_shr:1 row_mask:0xf bank_mask:0xf
	v_mov_b32_dpp v63, v29 row_shr:2 row_mask:0xf bank_mask:0xf
	v_mov_b32_dpp v46, v29 row_ror:1 row_mask:0xf bank_mask:0xf
	v_mov_b32_dpp v47, v29 row_ror:2 row_mask:0xf bank_mask:0xf
	v_mov_b32_dpp v56, v30 row_shr:1 row_mask:0xf bank_mask:0xf
	v_mov_b32_dpp v57, v30 row_shr:2 row_mask:0xf bank_mask:0xf
	v_mov_b32_dpp v40, v30 row_ror:1 row_mask:0xf bank_mask:0xf
	v_mov_b32_dpp v41, v30 row_ror:2 row_mask:0xf bank_mask:0xf
	v_mov_b32_dpp v58, v31 row_shr:1 row_mask:0xf bank_mask:0xf
	v_mov_b32_dpp v59, v31 row_shr:2 row_mask:0xf bank_mask:0xf
	v_mov_b32_dpp v42, v31 row_ror:1 row_mask:0xf bank_mask:0xf
	v_mov_b32_dpp v43, v31 row_ror:2 row_mask:0xf bank_mask:0xf
	v_mov_b32_dpp v52, v24 row_shr:1 row_mask:0xf bank_mask:0xf
	v_mov_b32_dpp v53, v24 row_shr:2 row_mask:0xf bank_mask:0xf
	v_mov_b32_dpp v36, v24 row_ror:1 row_mask:0xf bank_mask:0xf
	v_mov_b32_dpp v37, v24 row_ror:2 row_mask:0xf bank_mask:0xf
	v_mov_b32_dpp v54, v25 row_shr:1 row_mask:0xf bank_mask:0xf
	v_mov_b32_dpp v55, v25 row_shr:2 row_mask:0xf bank_mask:0xf
	v_mov_b32_dpp v38, v25 row_ror:1 row_mask:0xf bank_mask:0xf
	v_mov_b32_dpp v39, v25 row_ror:2 row_mask:0xf bank_mask:0xf
	v_mov_b32_dpp v48, v26 row_shr:1 row_mask:0xf bank_mask:0xf
	v_mov_b32_dpp v49, v26 row_shr:2 row_mask:0xf bank_mask:0xf
	v_mov_b32_dpp v32, v26 row_ror:1 row_mask:0xf bank_mask:0xf
	v_mov_b32_dpp v33, v26 row_ror:2 row_mask:0xf bank_mask:0xf
	v_mov_b32_dpp v50, v27 row_shr:1 row_mask:0xf bank_mask:0xf
	v_mov_b32_dpp v51, v27 row_shr:2 row_mask:0xf bank_mask:0xf
	v_mov_b32_dpp v34, v27 row_ror:1 row_mask:0xf bank_mask:0xf
	v_mov_b32_dpp v35, v27 row_ror:2 row_mask:0xf bank_mask:0xf
	v_cmp_gt_i32_e32 vcc, s28, v88
	s_and_saveexec_b64 s[26:27], vcc
	s_cbranch_execz .LBB0_823
	v_and_b32_e32 v89, 0x3fff, v88
	v_cmp_gt_u32_e64 s[0:1], 2, v89
	v_cmp_eq_u32_e32 vcc, 0, v89
	s_nop 0
	v_pk_fma_f32 v[28:29], v[28:29], v[92:93], v[96:97]
	v_cndmask_b32_e64 v90, v61, 0, s[0:1]
	v_cndmask_b32_e64 v61, v62, 0, vcc
	v_cndmask_b32_e64 v60, v60, 0, vcc
	v_cndmask_b32_e64 v91, v63, 0, s[0:1]
	v_pk_fma_f32 v[28:29], v[84:85], v[60:61], v[28:29]
	v_pk_fma_f32 v[30:31], v[30:31], v[94:95], v[98:99]
	v_cndmask_b32_e64 v62, v57, 0, s[0:1]
	v_cndmask_b32_e64 v57, v58, 0, vcc
	v_cndmask_b32_e64 v56, v56, 0, vcc
	v_pk_fma_f32 v[28:29], v[80:81], v[90:91], v[28:29]
	v_cndmask_b32_e64 v63, v59, 0, s[0:1]
	v_pk_fma_f32 v[30:31], v[86:87], v[56:57], v[30:31]
	v_mul_f32_e32 v60, 0xbfb8aa3b, v28
	v_mul_f32_e32 v61, 0xbfb8aa3b, v29
	v_pk_fma_f32 v[30:31], v[82:83], v[62:63], v[30:31]
	v_exp_f32_e32 v60, v60
	v_exp_f32_e32 v61, v61
	v_mul_f32_e32 v56, 0xbfb8aa3b, v30
	v_mul_f32_e32 v57, 0xbfb8aa3b, v31
	v_exp_f32_e32 v56, v56
	v_exp_f32_e32 v57, v57
	v_add_f32_e32 v60, 1.0, v60
	v_add_f32_e32 v61, 1.0, v61
	v_rcp_f32_e32 v60, v60
	v_rcp_f32_e32 v61, v61
	v_add_f32_e32 v56, 1.0, v56
	v_add_f32_e32 v57, 1.0, v57
	v_rcp_f32_e32 v56, v56
	v_rcp_f32_e32 v57, v57
	v_pk_mul_f32 v[28:29], v[28:29], v[60:61]
	v_pk_fma_f32 v[24:25], v[24:25], v[72:73], v[76:77]
	v_pk_mul_f32 v[20:21], v[20:21], v[28:29]
	v_pk_mul_f32 v[28:29], v[30:31], v[56:57]
	v_cvt_pk_bf16_f32 v20, v20, v21
	v_pk_mul_f32 v[22:23], v[22:23], v[28:29]
	v_cndmask_b32_e64 v29, v54, 0, vcc
	v_cndmask_b32_e64 v28, v52, 0, vcc
	v_cvt_pk_bf16_f32 v21, v22, v23
	v_cndmask_b32_e64 v23, v55, 0, s[0:1]
	v_cndmask_b32_e64 v22, v53, 0, s[0:1]
	v_pk_fma_f32 v[24:25], v[68:69], v[28:29], v[24:25]
	v_cndmask_b32_e64 v31, v50, 0, vcc
	v_pk_fma_f32 v[22:23], v[64:65], v[22:23], v[24:25]
	v_cndmask_b32_e64 v30, v48, 0, vcc
	v_mul_f32_e32 v24, 0xbfb8aa3b, v22
	v_exp_f32_e32 v28, v24
	v_mul_f32_e32 v24, 0xbfb8aa3b, v23
	v_exp_f32_e32 v29, v24
	v_pk_fma_f32 v[24:25], v[26:27], v[74:75], v[78:79]
	v_add_f32_e32 v26, 1.0, v28
	v_cndmask_b32_e64 v28, v49, 0, s[0:1]
	v_add_f32_e32 v27, 1.0, v29
	v_cndmask_b32_e64 v29, v51, 0, s[0:1]
	v_pk_fma_f32 v[24:25], v[70:71], v[30:31], v[24:25]
	v_rcp_f32_e32 v26, v26
	v_pk_fma_f32 v[24:25], v[66:67], v[28:29], v[24:25]
	v_rcp_f32_e32 v27, v27
	v_mul_f32_e32 v28, 0xbfb8aa3b, v24
	v_mul_f32_e32 v29, 0xbfb8aa3b, v25
	v_exp_f32_e32 v28, v28
	v_exp_f32_e32 v29, v29
	v_pk_mul_f32 v[22:23], v[22:23], v[26:27]
	v_add_f32_e32 v28, 1.0, v28
	v_add_f32_e32 v29, 1.0, v29
	v_rcp_f32_e32 v28, v28
	v_rcp_f32_e32 v29, v29
	v_pk_mul_f32 v[16:17], v[16:17], v[22:23]
	s_nop 0
	v_cvt_pk_bf16_f32 v22, v16, v17
	v_pk_mul_f32 v[16:17], v[24:25], v[28:29]
	s_nop 0
	v_pk_mul_f32 v[16:17], v[18:19], v[16:17]
	s_nop 0
	v_cvt_pk_bf16_f32 v23, v16, v17
	v_mov_b64_e32 v[16:17], s[60:61]
	v_mad_i64_i32 v[16:17], s[0:1], v88, s29, v[16:17]
	v_lshl_add_u64 v[16:17], v[180:181], 1, v[16:17]
	global_store_dwordx4 v[16:17], v[20:23], off
